# GEMM tile heads: accumulator zero-init with 64 v_mov_b64 instead of 127 v_mov_b32 (5 GEMM phases)
# speedup vs baseline: 1.0064x; 1.0064x over previous
; template <class Epi, class Sched, bool ALIGN_EPI = false, bool SP2 = false>
; __device__ __forceinline__ void gemm_phase(PG8_LAS unsigned char* lds, const Gemm g, const Sched& S, const Epi& E, const int tid) {
;     ...
;     for (;;) {
;         const bool has_next = S.next(ui + 1, nxt);
;         const char* nA = has_next ? (const char*)g.A + (size_t)nxt.pm * tstep : cA; const char* nB = has_next ? (const char*)g.Bt + (size_t)nxt.pn * tstep : cB;
;     ...
; #pragma unroll
;         for (int a = 0; a < 2; ++a)
; #pragma unroll
;             for (int b = 0; b < 2; ++b)
; #pragma unroll
;                 for (int m = 0; m < 4; ++m)
; #pragma unroll
;                     for (int n = 0; n < 2; ++n) acc[a][b][m][n] = (f32x4){0.f, 0.f, 0.f, 0.f};
;         cur = nxt; cA = nA; cB = nB; ++ui;
.LBB0_98:
	s_ashr_i32 s13, s12, 31
	s_lshl_b64 s[14:15], s[12:13], 19
	s_add_u32 s14, s27, s14
	s_addc_u32 s15, s34, s15
	s_and_b64 s[16:17], s[2:3], exec
	s_cselect_b32 s13, s15, s19
	s_cselect_b32 s45, s14, s18
	s_ashr_i32 s11, s10, 31
	s_lshl_b64 s[16:17], s[10:11], 19
	s_add_u32 s16, s24, s16
	s_addc_u32 s17, s25, s17
	s_and_b64 s[22:23], s[2:3], exec
	s_cselect_b32 s11, s17, s21
	s_cselect_b32 s46, s16, s20
	s_add_u32 s18, s18, 0x40080
	s_addc_u32 s19, s19, 0
	s_add_u32 s47, s20, 0x100
	v_mov_b32_e32 v4, 0
	s_addc_u32 s48, s21, 0
	s_mov_b32 s49, -2
	v_mov_b64_e32 v[4:5], 0
	v_mov_b64_e32 v[6:7], 0
	v_mov_b64_e32 v[8:9], 0
	v_mov_b64_e32 v[10:11], 0
	v_mov_b64_e32 v[12:13], 0
	v_mov_b64_e32 v[14:15], 0
	v_mov_b64_e32 v[16:17], 0
	v_mov_b64_e32 v[18:19], 0
	v_mov_b64_e32 v[20:21], 0
	v_mov_b64_e32 v[22:23], 0
	v_mov_b64_e32 v[24:25], 0
	v_mov_b64_e32 v[26:27], 0
	v_mov_b64_e32 v[28:29], 0
	v_mov_b64_e32 v[30:31], 0
	v_mov_b64_e32 v[32:33], 0
	v_mov_b64_e32 v[34:35], 0
	v_mov_b64_e32 v[36:37], 0
	v_mov_b64_e32 v[38:39], 0
	v_mov_b64_e32 v[40:41], 0
	v_mov_b64_e32 v[42:43], 0
	v_mov_b64_e32 v[44:45], 0
	v_mov_b64_e32 v[46:47], 0
	v_mov_b64_e32 v[48:49], 0
	v_mov_b64_e32 v[50:51], 0
	v_mov_b64_e32 v[52:53], 0
	v_mov_b64_e32 v[54:55], 0
	v_mov_b64_e32 v[56:57], 0
	v_mov_b64_e32 v[58:59], 0
	v_mov_b64_e32 v[60:61], 0
	v_mov_b64_e32 v[62:63], 0
	v_mov_b64_e32 v[64:65], 0
	v_mov_b64_e32 v[66:67], 0
	v_mov_b64_e32 v[68:69], 0
	v_mov_b64_e32 v[70:71], 0
	v_mov_b64_e32 v[72:73], 0
	v_mov_b64_e32 v[74:75], 0
	v_mov_b64_e32 v[76:77], 0
	v_mov_b64_e32 v[78:79], 0
	v_mov_b64_e32 v[80:81], 0
	v_mov_b64_e32 v[82:83], 0
	v_mov_b64_e32 v[84:85], 0
	v_mov_b64_e32 v[86:87], 0
	v_mov_b64_e32 v[88:89], 0
	v_mov_b64_e32 v[90:91], 0
	v_mov_b64_e32 v[92:93], 0
	v_mov_b64_e32 v[94:95], 0
	v_mov_b64_e32 v[96:97], 0
	v_mov_b64_e32 v[98:99], 0
	v_mov_b64_e32 v[100:101], 0
	v_mov_b64_e32 v[102:103], 0
	v_mov_b64_e32 v[104:105], 0
	v_mov_b64_e32 v[106:107], 0
	v_mov_b64_e32 v[108:109], 0
	v_mov_b64_e32 v[110:111], 0
	v_mov_b64_e32 v[112:113], 0
	v_mov_b64_e32 v[114:115], 0
	v_mov_b64_e32 v[128:129], 0
	v_mov_b64_e32 v[130:131], 0
	v_mov_b64_e32 v[136:137], 0
	v_mov_b64_e32 v[138:139], 0
	v_mov_b64_e32 v[140:141], 0
	v_mov_b64_e32 v[142:143], 0
	v_mov_b64_e32 v[144:145], 0
	v_mov_b64_e32 v[146:147], 0

; template <class Epi, class Sched, bool ALIGN_EPI = false, bool SP2 = false>
; __device__ __forceinline__ void gemm_phase(PG8_LAS unsigned char* lds, const Gemm g, const Sched& S, const Epi& E, const int tid) {
;     ...
;     for (;;) {
;         const bool has_next = S.next(ui + 1, nxt);
;         const char* nA = has_next ? (const char*)g.A + (size_t)nxt.pm * tstep : cA; const char* nB = has_next ? (const char*)g.Bt + (size_t)nxt.pn * tstep : cB;
;     ...
; #pragma unroll
;         for (int a = 0; a < 2; ++a)
; #pragma unroll
;             for (int b = 0; b < 2; ++b)
; #pragma unroll
;                 for (int m = 0; m < 4; ++m)
; #pragma unroll
;                     for (int n = 0; n < 2; ++n) acc[a][b][m][n] = (f32x4){0.f, 0.f, 0.f, 0.f};
;         cur = nxt; cA = nA; cB = nB; ++ui;
.LBB0_292:
	s_ashr_i32 s17, s16, 31
	s_lshl_b64 s[18:19], s[16:17], 19
	s_add_u32 s18, s34, s18
	s_addc_u32 s19, s40, s19
	s_and_b64 s[20:21], s[4:5], exec
	s_cselect_b32 s17, s19, s3
	s_cselect_b32 s23, s18, s2
	s_ashr_i32 s15, s14, 31
	s_lshl_b64 s[20:21], s[14:15], 19
	s_add_u32 s20, s41, s20
	s_addc_u32 s21, s42, s21
	s_and_b64 s[36:37], s[4:5], exec
	s_cselect_b32 s15, s21, s27
	s_cselect_b32 s51, s20, s26
	s_add_u32 s2, s2, 0x40080
	s_addc_u32 s3, s3, 0
	s_add_u32 s52, s26, 0x100
	v_mov_b32_e32 v12, 0
	s_addc_u32 s53, s27, 0
	s_mov_b32 s54, -2
	v_mov_b64_e32 v[4:5], 0
	v_mov_b64_e32 v[6:7], 0
	v_mov_b64_e32 v[8:9], 0
	v_mov_b64_e32 v[10:11], 0
	v_mov_b64_e32 v[12:13], 0
	v_mov_b64_e32 v[14:15], 0
	v_mov_b64_e32 v[16:17], 0
	v_mov_b64_e32 v[18:19], 0
	v_mov_b64_e32 v[20:21], 0
	v_mov_b64_e32 v[22:23], 0
	v_mov_b64_e32 v[24:25], 0
	v_mov_b64_e32 v[26:27], 0
	v_mov_b64_e32 v[28:29], 0
	v_mov_b64_e32 v[30:31], 0
	v_mov_b64_e32 v[32:33], 0
	v_mov_b64_e32 v[34:35], 0
	v_mov_b64_e32 v[36:37], 0
	v_mov_b64_e32 v[38:39], 0
	v_mov_b64_e32 v[40:41], 0
	v_mov_b64_e32 v[42:43], 0
	v_mov_b64_e32 v[44:45], 0
	v_mov_b64_e32 v[46:47], 0
	v_mov_b64_e32 v[48:49], 0
	v_mov_b64_e32 v[50:51], 0
	v_mov_b64_e32 v[52:53], 0
	v_mov_b64_e32 v[54:55], 0
	v_mov_b64_e32 v[56:57], 0
	v_mov_b64_e32 v[58:59], 0
	v_mov_b64_e32 v[60:61], 0
	v_mov_b64_e32 v[62:63], 0
	v_mov_b64_e32 v[64:65], 0
	v_mov_b64_e32 v[66:67], 0
	v_mov_b64_e32 v[68:69], 0
	v_mov_b64_e32 v[70:71], 0
	v_mov_b64_e32 v[72:73], 0
	v_mov_b64_e32 v[74:75], 0
	v_mov_b64_e32 v[76:77], 0
	v_mov_b64_e32 v[78:79], 0
	v_mov_b64_e32 v[80:81], 0
	v_mov_b64_e32 v[82:83], 0
	v_mov_b64_e32 v[84:85], 0
	v_mov_b64_e32 v[86:87], 0
	v_mov_b64_e32 v[88:89], 0
	v_mov_b64_e32 v[90:91], 0
	v_mov_b64_e32 v[92:93], 0
	v_mov_b64_e32 v[94:95], 0
	v_mov_b64_e32 v[96:97], 0
	v_mov_b64_e32 v[98:99], 0
	v_mov_b64_e32 v[100:101], 0
	v_mov_b64_e32 v[102:103], 0
	v_mov_b64_e32 v[104:105], 0
	v_mov_b64_e32 v[106:107], 0
	v_mov_b64_e32 v[108:109], 0
	v_mov_b64_e32 v[110:111], 0
	v_mov_b64_e32 v[112:113], 0
	v_mov_b64_e32 v[114:115], 0
	v_mov_b64_e32 v[116:117], 0
	v_mov_b64_e32 v[118:119], 0
	v_mov_b64_e32 v[120:121], 0
	v_mov_b64_e32 v[122:123], 0
	v_mov_b64_e32 v[124:125], 0
	v_mov_b64_e32 v[126:127], 0
	v_mov_b64_e32 v[128:129], 0
	v_mov_b64_e32 v[130:131], 0

; template <class Epi, class Sched, bool ALIGN_EPI = false, bool SP2 = false>
; __device__ __forceinline__ void gemm_phase(PG8_LAS unsigned char* lds, const Gemm g, const Sched& S, const Epi& E, const int tid) {
;     ...
;     for (;;) {
;         const bool has_next = S.next(ui + 1, nxt);
;         const char* nA = has_next ? (const char*)g.A + (size_t)nxt.pm * tstep : cA; const char* nB = has_next ? (const char*)g.Bt + (size_t)nxt.pn * tstep : cB;
;     ...
; #pragma unroll
;         for (int a = 0; a < 2; ++a)
; #pragma unroll
;             for (int b = 0; b < 2; ++b)
; #pragma unroll
;                 for (int m = 0; m < 4; ++m)
; #pragma unroll
;                     for (int n = 0; n < 2; ++n) acc[a][b][m][n] = (f32x4){0.f, 0.f, 0.f, 0.f};
;         cur = nxt; cA = nA; cB = nB; ++ui;
.LBB0_475:
	s_add_u32 s6, s6, 0x80
	s_addc_u32 s7, s7, 0
	s_add_u32 s78, s58, 0x100
	v_mov_b32_e32 v4, 0
	s_addc_u32 s79, s59, 0
	s_mov_b32 s58, 0
	v_mov_b64_e32 v[4:5], 0
	v_mov_b64_e32 v[6:7], 0
	v_mov_b64_e32 v[8:9], 0
	v_mov_b64_e32 v[10:11], 0
	v_mov_b64_e32 v[12:13], 0
	v_mov_b64_e32 v[14:15], 0
	v_mov_b64_e32 v[16:17], 0
	v_mov_b64_e32 v[18:19], 0
	v_mov_b64_e32 v[20:21], 0
	v_mov_b64_e32 v[22:23], 0
	v_mov_b64_e32 v[24:25], 0
	v_mov_b64_e32 v[26:27], 0
	v_mov_b64_e32 v[28:29], 0
	v_mov_b64_e32 v[30:31], 0
	v_mov_b64_e32 v[32:33], 0
	v_mov_b64_e32 v[34:35], 0
	v_mov_b64_e32 v[36:37], 0
	v_mov_b64_e32 v[38:39], 0
	v_mov_b64_e32 v[40:41], 0
	v_mov_b64_e32 v[42:43], 0
	v_mov_b64_e32 v[44:45], 0
	v_mov_b64_e32 v[46:47], 0
	v_mov_b64_e32 v[48:49], 0
	v_mov_b64_e32 v[50:51], 0
	v_mov_b64_e32 v[52:53], 0
	v_mov_b64_e32 v[54:55], 0
	v_mov_b64_e32 v[56:57], 0
	v_mov_b64_e32 v[58:59], 0
	v_mov_b64_e32 v[60:61], 0
	v_mov_b64_e32 v[62:63], 0
	v_mov_b64_e32 v[64:65], 0
	v_mov_b64_e32 v[66:67], 0
	v_mov_b64_e32 v[68:69], 0
	v_mov_b64_e32 v[70:71], 0
	v_mov_b64_e32 v[72:73], 0
	v_mov_b64_e32 v[74:75], 0
	v_mov_b64_e32 v[76:77], 0
	v_mov_b64_e32 v[78:79], 0
	v_mov_b64_e32 v[80:81], 0
	v_mov_b64_e32 v[82:83], 0
	v_mov_b64_e32 v[84:85], 0
	v_mov_b64_e32 v[86:87], 0
	v_mov_b64_e32 v[88:89], 0
	v_mov_b64_e32 v[90:91], 0
	v_mov_b64_e32 v[92:93], 0
	v_mov_b64_e32 v[94:95], 0
	v_mov_b64_e32 v[96:97], 0
	v_mov_b64_e32 v[98:99], 0
	v_mov_b64_e32 v[100:101], 0
	v_mov_b64_e32 v[102:103], 0
	v_mov_b64_e32 v[104:105], 0
	v_mov_b64_e32 v[106:107], 0
	v_mov_b64_e32 v[108:109], 0
	v_mov_b64_e32 v[110:111], 0
	v_mov_b64_e32 v[112:113], 0
	v_mov_b64_e32 v[114:115], 0
	v_mov_b64_e32 v[116:117], 0
	v_mov_b64_e32 v[118:119], 0
	v_mov_b64_e32 v[120:121], 0
	v_mov_b64_e32 v[122:123], 0
	v_mov_b64_e32 v[124:125], 0
	v_mov_b64_e32 v[126:127], 0
	v_mov_b64_e32 v[128:129], 0
	v_mov_b64_e32 v[130:131], 0

; template <class Epi, class Sched, bool ALIGN_EPI = false, bool SP2 = false>
; __device__ __forceinline__ void gemm_phase(PG8_LAS unsigned char* lds, const Gemm g, const Sched& S, const Epi& E, const int tid) {
;     ...
;     for (;;) {
;         const bool has_next = S.next(ui + 1, nxt);
;         const char* nA = has_next ? (const char*)g.A + (size_t)nxt.pm * tstep : cA; const char* nB = has_next ? (const char*)g.Bt + (size_t)nxt.pn * tstep : cB;
;     ...
; #pragma unroll
;         for (int a = 0; a < 2; ++a)
; #pragma unroll
;             for (int b = 0; b < 2; ++b)
; #pragma unroll
;                 for (int m = 0; m < 4; ++m)
; #pragma unroll
;                     for (int n = 0; n < 2; ++n) acc[a][b][m][n] = (f32x4){0.f, 0.f, 0.f, 0.f};
;         cur = nxt; cA = nA; cB = nB; ++ui;
.LBB0_521:
	s_ashr_i32 s13, s12, 31
	s_lshl_b64 s[14:15], s[12:13], 19
	s_add_u32 s14, s26, s14
	s_addc_u32 s15, s27, s15
	s_and_b64 s[16:17], s[2:3], exec
	s_cselect_b32 s13, s15, s19
	s_cselect_b32 s47, s14, s18
	s_ashr_i32 s11, s10, 31
	s_lshl_b64 s[16:17], s[10:11], 19
	s_add_u32 s16, s34, s16
	s_addc_u32 s17, s36, s17
	s_and_b64 s[22:23], s[2:3], exec
	s_cselect_b32 s11, s17, s21
	s_cselect_b32 s48, s16, s20
	s_add_u32 s18, s18, 0x40080
	s_addc_u32 s19, s19, 0
	s_add_u32 s49, s20, 0x100
	v_mov_b32_e32 v4, 0
	s_addc_u32 s50, s21, 0
	s_mov_b32 s51, -2
	v_mov_b64_e32 v[4:5], 0
	v_mov_b64_e32 v[6:7], 0
	v_mov_b64_e32 v[8:9], 0
	v_mov_b64_e32 v[10:11], 0
	v_mov_b64_e32 v[12:13], 0
	v_mov_b64_e32 v[14:15], 0
	v_mov_b64_e32 v[16:17], 0
	v_mov_b64_e32 v[18:19], 0
	v_mov_b64_e32 v[20:21], 0
	v_mov_b64_e32 v[22:23], 0
	v_mov_b64_e32 v[24:25], 0
	v_mov_b64_e32 v[26:27], 0
	v_mov_b64_e32 v[28:29], 0
	v_mov_b64_e32 v[30:31], 0
	v_mov_b64_e32 v[32:33], 0
	v_mov_b64_e32 v[34:35], 0
	v_mov_b64_e32 v[36:37], 0
	v_mov_b64_e32 v[38:39], 0
	v_mov_b64_e32 v[40:41], 0
	v_mov_b64_e32 v[42:43], 0
	v_mov_b64_e32 v[44:45], 0
	v_mov_b64_e32 v[46:47], 0
	v_mov_b64_e32 v[48:49], 0
	v_mov_b64_e32 v[50:51], 0
	v_mov_b64_e32 v[52:53], 0
	v_mov_b64_e32 v[54:55], 0
	v_mov_b64_e32 v[56:57], 0
	v_mov_b64_e32 v[58:59], 0
	v_mov_b64_e32 v[60:61], 0
	v_mov_b64_e32 v[62:63], 0
	v_mov_b64_e32 v[64:65], 0
	v_mov_b64_e32 v[66:67], 0
	v_mov_b64_e32 v[68:69], 0
	v_mov_b64_e32 v[70:71], 0
	v_mov_b64_e32 v[72:73], 0
	v_mov_b64_e32 v[74:75], 0
	v_mov_b64_e32 v[76:77], 0
	v_mov_b64_e32 v[78:79], 0
	v_mov_b64_e32 v[80:81], 0
	v_mov_b64_e32 v[82:83], 0
	v_mov_b64_e32 v[84:85], 0
	v_mov_b64_e32 v[86:87], 0
	v_mov_b64_e32 v[88:89], 0
	v_mov_b64_e32 v[90:91], 0
	v_mov_b64_e32 v[92:93], 0
	v_mov_b64_e32 v[94:95], 0
	v_mov_b64_e32 v[96:97], 0
	v_mov_b64_e32 v[98:99], 0
	v_mov_b64_e32 v[100:101], 0
	v_mov_b64_e32 v[102:103], 0
	v_mov_b64_e32 v[104:105], 0
	v_mov_b64_e32 v[106:107], 0
	v_mov_b64_e32 v[108:109], 0
	v_mov_b64_e32 v[110:111], 0
	v_mov_b64_e32 v[112:113], 0
	v_mov_b64_e32 v[114:115], 0
	v_mov_b64_e32 v[116:117], 0
	v_mov_b64_e32 v[118:119], 0
	v_mov_b64_e32 v[120:121], 0
	v_mov_b64_e32 v[122:123], 0
	v_mov_b64_e32 v[124:125], 0
	v_mov_b64_e32 v[126:127], 0
	v_mov_b64_e32 v[128:129], 0
	v_mov_b64_e32 v[130:131], 0

; template <class Epi, class Sched, bool ALIGN_EPI = false, bool SP2 = false>
; __device__ __forceinline__ void gemm_phase(PG8_LAS unsigned char* lds, const Gemm g, const Sched& S, const Epi& E, const int tid) {
;     ...
;     for (;;) {
;         const bool has_next = S.next(ui + 1, nxt);
;         const char* nA = has_next ? (const char*)g.A + (size_t)nxt.pm * tstep : cA; const char* nB = has_next ? (const char*)g.Bt + (size_t)nxt.pn * tstep : cB;
;     ...
; #pragma unroll
;         for (int a = 0; a < 2; ++a)
; #pragma unroll
;             for (int b = 0; b < 2; ++b)
; #pragma unroll
;                 for (int m = 0; m < 4; ++m)
; #pragma unroll
;                     for (int n = 0; n < 2; ++n) acc[a][b][m][n] = (f32x4){0.f, 0.f, 0.f, 0.f};
;         cur = nxt; cA = nA; cB = nB; ++ui;
.LBB0_841:
	s_ashr_i32 s13, s12, 31
	s_lshl_b64 s[14:15], s[12:13], 19
	s_add_u32 s14, s34, s14
	s_addc_u32 s15, s36, s15
	s_and_b64 s[16:17], s[38:39], exec
	s_cselect_b32 s13, s15, s23
	s_cselect_b32 s19, s14, s22
	s_ashr_i32 s11, s10, 31
	s_lshl_b64 s[16:17], s[10:11], 19
	s_add_u32 s16, s4, s16
	s_addc_u32 s17, s5, s17
	s_and_b64 s[26:27], s[38:39], exec
	s_cselect_b32 s11, s17, s25
	s_cselect_b32 s46, s16, s24
	s_add_u32 s22, s22, 0x40080
	s_addc_u32 s23, s23, 0
	s_add_u32 s47, s24, 0x100
	v_mov_b32_e32 v4, 0
	s_addc_u32 s48, s25, 0
	s_mov_b32 s49, -2
	v_mov_b64_e32 v[4:5], 0
	v_mov_b64_e32 v[6:7], 0
	v_mov_b64_e32 v[8:9], 0
	v_mov_b64_e32 v[10:11], 0
	v_mov_b64_e32 v[12:13], 0
	v_mov_b64_e32 v[14:15], 0
	v_mov_b64_e32 v[16:17], 0
	v_mov_b64_e32 v[18:19], 0
	v_mov_b64_e32 v[20:21], 0
	v_mov_b64_e32 v[22:23], 0
	v_mov_b64_e32 v[24:25], 0
	v_mov_b64_e32 v[26:27], 0
	v_mov_b64_e32 v[28:29], 0
	v_mov_b64_e32 v[30:31], 0
	v_mov_b64_e32 v[32:33], 0
	v_mov_b64_e32 v[34:35], 0
	v_mov_b64_e32 v[36:37], 0
	v_mov_b64_e32 v[38:39], 0
	v_mov_b64_e32 v[40:41], 0
	v_mov_b64_e32 v[42:43], 0
	v_mov_b64_e32 v[44:45], 0
	v_mov_b64_e32 v[46:47], 0
	v_mov_b64_e32 v[48:49], 0
	v_mov_b64_e32 v[50:51], 0
	v_mov_b64_e32 v[52:53], 0
	v_mov_b64_e32 v[54:55], 0
	v_mov_b64_e32 v[56:57], 0
	v_mov_b64_e32 v[58:59], 0
	v_mov_b64_e32 v[60:61], 0
	v_mov_b64_e32 v[62:63], 0
	v_mov_b64_e32 v[64:65], 0
	v_mov_b64_e32 v[66:67], 0
	v_mov_b64_e32 v[68:69], 0
	v_mov_b64_e32 v[70:71], 0
	v_mov_b64_e32 v[72:73], 0
	v_mov_b64_e32 v[74:75], 0
	v_mov_b64_e32 v[76:77], 0
	v_mov_b64_e32 v[78:79], 0
	v_mov_b64_e32 v[80:81], 0
	v_mov_b64_e32 v[82:83], 0
	v_mov_b64_e32 v[84:85], 0
	v_mov_b64_e32 v[86:87], 0
	v_mov_b64_e32 v[88:89], 0
	v_mov_b64_e32 v[90:91], 0
	v_mov_b64_e32 v[92:93], 0
	v_mov_b64_e32 v[94:95], 0
	v_mov_b64_e32 v[96:97], 0
	v_mov_b64_e32 v[98:99], 0
	v_mov_b64_e32 v[100:101], 0
	v_mov_b64_e32 v[102:103], 0
	v_mov_b64_e32 v[104:105], 0
	v_mov_b64_e32 v[106:107], 0
	v_mov_b64_e32 v[108:109], 0
	v_mov_b64_e32 v[110:111], 0
	v_mov_b64_e32 v[112:113], 0
	v_mov_b64_e32 v[114:115], 0
	v_mov_b64_e32 v[116:117], 0
	v_mov_b64_e32 v[118:119], 0
	v_mov_b64_e32 v[120:121], 0
	v_mov_b64_e32 v[122:123], 0
	v_mov_b64_e32 v[124:125], 0
	v_mov_b64_e32 v[126:127], 0
	v_mov_b64_e32 v[128:129], 0
	v_mov_b64_e32 v[130:131], 0
